# phase 5: non-scan blocks (wkv_direct, fold, transposes, pool GEMM) start at priority 2 over the co-resident scan waves
# baseline (speedup 1.0000x reference)
.LBB0_795:
	s_setprio 0
	s_cmp_lt_i32 s93, 7
	s_cbranch_scc0 .LBB0_840
	s_branch .LBB0_893
.LBB0_796:
	s_setprio 2
	s_sub_i32 s3, s94, 64
	s_sub_i32 s10, s2, 64
	s_cmpk_gt_i32 s10, 0xff
	s_cbranch_scc1 .LBB0_811
	v_mbcnt_lo_u32_b32 v0, -1, 0
	v_mbcnt_hi_u32_b32 v0, -1, v0
	v_and_b32_e32 v1, 64, v0
	v_add_u32_e32 v1, 64, v1
	v_xor_b32_e32 v2, 32, v0
	v_cmp_lt_i32_e32 vcc, v2, v1
	v_mul_u32_u24_e32 v212, 0x500, v214
	v_and_b32_e32 v188, 63, v218
	v_cndmask_b32_e32 v2, v0, v2, vcc
	v_lshlrev_b32_e32 v213, 2, v2
	v_xor_b32_e32 v2, 16, v0
	v_cmp_lt_i32_e32 vcc, v2, v1
	s_add_u32 s6, s84, 0x1080000
	v_or_b32_e32 v189, 64, v214
	v_cndmask_b32_e32 v2, v0, v2, vcc
	v_lshlrev_b32_e32 v215, 2, v2
	v_xor_b32_e32 v2, 8, v0
	v_cmp_lt_i32_e32 vcc, v2, v1
	v_mov_b32_e32 v191, 0
	v_lshl_or_b32 v221, v188, 2, v212
	v_cndmask_b32_e32 v2, v0, v2, vcc
	v_lshlrev_b32_e32 v216, 2, v2
	v_xor_b32_e32 v2, 4, v0
	v_cmp_lt_i32_e32 vcc, v2, v1
	s_addc_u32 s7, s85, 0
	v_mov_b32_e32 v222, 0x260
	v_cndmask_b32_e32 v2, v0, v2, vcc
	v_lshlrev_b32_e32 v217, 2, v2
	v_xor_b32_e32 v2, 2, v0
	v_cmp_lt_i32_e32 vcc, v2, v1
	v_mov_b32_e32 v223, 0x3a27c5ac
	v_mov_b32_e32 v224, 0x4000
	v_cndmask_b32_e32 v2, v0, v2, vcc
	v_lshlrev_b32_e32 v219, 2, v2
	v_xor_b32_e32 v2, 1, v0
	v_cmp_lt_i32_e32 vcc, v2, v1
	v_mov_b32_e32 v193, 1.0
	v_mov_b32_e32 v225, 0x442a000
	v_cndmask_b32_e32 v0, v0, v2, vcc
	v_lshlrev_b32_e32 v220, 2, v0
	v_mov_b32_e32 v226, 0x420e000
	s_mov_b32 s11, s10
